# odd-layer attention (MLA+GQA): softmax reference folded into first QK MFMA C operand (shared max of two row refs), 64 v_sub per tile removed
# speedup vs baseline: 1.0241x; 1.0241x over previous
; #define LOADKV(t) do { \
;     _Pragma("unroll") for (int j = 0; j < NKC; ++j) if (j + 1 < NKC || k1) rk[j] = *(const u32x4*)(kh + (size_t)(t) * 64 * DQK + (size_t)(tid + 512 * j) * 8); \
;     _Pragma("unroll") for (int j = 0; j < NVC; ++j) rv[j] = *(const u32x4*)(vg0 + (size_t)(64 * j) * S + (size_t)(t) * 64); } while (0)
; #pragma unroll
;   for (int sl = 0; sl < 8; ++sl) m = max(m, kmx[sl * 64 + idx]);
;   return sqrtf(__uint_as_float(m)); }
; template <int DQK, int DV>
; __device__ __forceinline__ void attn_pass2(const bf16_t* __restrict__ qh, const bf16_t* __restrict__ kh, const bf16_t* __restrict__ vth, int q0, char* smem, f32x16 (&o)[2][DV / 32], float kmax, int wvp) {
;     ...
;   bf16x8 qf[2][NKS];
; #pragma unroll
;   for (int qb = 0; qb < 2; ++qb) {
;     const bf16_t* qrow = qh + (size_t)(q0 + 64 * wid + 32 * qb + r) * DQK + 8 * h;
; #pragma unroll
;     for (int ks = 0; ks < NKS; ++ks) qf[qb][ks] = *(const bf16x8*)(qrow + 16 * ks);
;   }
;   int klo[NKC], vlo[NVC];
;   const bf16_t* vg0 = vth + (size_t)(tid >> 3) * S + (tid & 7) * 8;
; #pragma unroll
;   for (int j = 0; j < NKC; ++j) { const int c = tid + 512 * j; klo[j] = (c / CK) * KP + (c % CK) * 16; }
; #pragma unroll
;   for (int j = 0; j < NVC; ++j) { const int c = tid + 512 * j; vlo[j] = (c >> 3) * VP + (c & 7) * 16; }
;   u32x4 rk[NKC], rv[NVC];
;   const bool k1 = (TKC % 512 == 0) || (tid < TKC % 512);
;     ...
;   LOADKV(0);
; #pragma unroll
;   for (int qb = 0; qb < 2; ++qb)
; #pragma unroll
;     for (int eb = 0; eb < NEB; ++eb)
; #pragma unroll
;       for (int i = 0; i < 16; ++i) o[qb][eb][i] = 0.f;
;   float l_run[2] = {0.f, 0.f}, mref[2];
; #pragma unroll
;   for (int qb = 0; qb < 2; ++qb) {
;     float qq = 0.f;
; #pragma unroll
;     for (int ks = 0; ks < NKS; ++ks)
; #pragma unroll
;       for (int j = 0; j < 8; ++j) { const float t = bf2f((unsigned short)qf[qb][ks][j]); qq += t * t; }
;     { auto rr = __builtin_amdgcn_permlane32_swap(__float_as_uint(qq), __float_as_uint(qq), false, false); qq = __uint_as_float(rr[0]) + __uint_as_float(rr[1]); }
;     mref[qb] = sqrtf(qq) * kmax * 1.01f + 0.01f;
;   }
.LBB0_1427:
	s_cmpk_gt_i32 s75, 0xff
	s_mov_b64 s[6:7], -1
	s_cbranch_scc0 .LBB0_1434
	s_bfe_u32 s11, s75, 0x10003
	s_lshl_b32 s7, s74, 18
	s_lshl_b32 s6, s11, 21
	s_and_b32 s7, s7, 0x100000
	s_or_b32 s13, s6, s7
	s_lshl_b32 s7, s75, 20
	s_and_b32 s10, s75, 7
	s_bfe_u32 s6, s75, 0x10002
	s_and_b32 s7, s7, 0xf00000
	v_readlane_b32 s8, v252, 14
	s_add_u32 s14, s8, s7
	v_readlane_b32 s7, v252, 16
	s_addc_u32 s15, s7, 0
	s_lshl_b32 s7, s11, 1
	s_or_b32 s16, s7, s6
	s_lshl_b32 s6, s16, 20
	v_readlane_b32 s7, v252, 4
	s_add_u32 s8, s7, s6
	v_readlane_b32 s7, v252, 6
	s_addc_u32 s9, s7, 0
	v_readlane_b32 s18, v252, 17
	v_readlane_b32 s19, v252, 18
	s_add_u32 s6, s18, s6
	s_addc_u32 s7, s19, 0
	s_lshl_b32 s16, s16, 2
	s_lshl_b32 s12, s75, 5
	v_mov_b32_e32 v0, s16
	s_and_b32 s12, s12, 0x7ffffe00
	global_load_dword v20, v0, s[46:47] offset:128
	global_load_dword v21, v0, s[46:47] offset:384
	global_load_dword v22, v0, s[46:47] offset:640
	global_load_dword v23, v0, s[46:47] offset:896
	global_load_dword v24, v0, s[46:47] offset:1152
	global_load_dword v25, v0, s[46:47] offset:1408
	global_load_dword v26, v0, s[46:47] offset:1664
	global_load_dword v27, v0, s[46:47] offset:1920
	v_mbcnt_lo_u32_b32 v0, -1, 0
	v_mbcnt_hi_u32_b32 v0, -1, v0
	s_addk_i32 s12, 0xe000
	v_add_u32_e32 v2, s27, v0
	v_mov_b32_e32 v9, v191
	v_and_b32_e32 v0, 0xffffffc0, v2
	v_and_b32_e32 v28, 31, v2
	v_add_u32_e32 v0, s12, v0
	v_or_b32_e32 v12, v0, v28
	v_lshrrev_b32_e32 v29, 1, v2
	v_and_b32_e32 v190, 16, v29
	v_ashrrev_i32_e32 v13, 31, v12
	v_lshl_add_u64 v[14:15], s[14:15], 0, v[190:191]
	v_lshlrev_b64 v[0:1], 7, v[12:13]
	v_lshl_add_u64 v[16:17], v[14:15], 0, v[0:1]
	global_load_dwordx4 v[128:131], v[16:17], off
	global_load_dwordx4 v[132:135], v[16:17], off offset:32
	global_load_dwordx4 v[136:139], v[16:17], off offset:64
	global_load_dwordx4 v[140:143], v[16:17], off offset:96
	v_or_b32_e32 v18, 32, v12
	v_ashrrev_i32_e32 v19, 31, v18
	v_lshlrev_b64 v[16:17], 7, v[18:19]
	v_lshl_add_u64 v[14:15], v[14:15], 0, v[16:17]
	global_load_dwordx4 v[144:147], v[14:15], off
	global_load_dwordx4 v[148:151], v[14:15], off offset:32
	global_load_dwordx4 v[152:155], v[14:15], off offset:64
	global_load_dwordx4 v[156:159], v[14:15], off offset:96
	v_ashrrev_i32_e32 v10, 3, v2
	v_ashrrev_i32_e32 v11, 31, v10
	v_lshlrev_b32_e32 v1, 4, v2
	v_lshlrev_b64 v[4:5], 14, v[10:11]
	v_and_b32_e32 v8, 0x70, v1
	v_lshl_add_u64 v[12:13], s[6:7], 0, v[4:5]
	v_lshl_add_u64 v[12:13], v[12:13], 0, v[8:9]
	v_ashrrev_i32_e32 v3, 31, v2
	v_lshlrev_b64 v[6:7], 4, v[2:3]
	v_lshrrev_b32_e32 v1, 29, v3
	v_add_u32_e32 v1, v2, v1
	v_lshrrev_b32_e32 v3, 3, v1
	v_and_b32_e32 v1, 0xffffff8, v1
	v_mul_lo_u32 v3, v3, s37
	v_sub_u32_e32 v1, v2, v1
	s_waitcnt vmcnt(32)
	v_lshl_add_u32 v184, v1, 4, v3
	v_lshlrev_b32_e32 v3, 1, v2
	v_and_b32_e32 v1, 19, v2
	v_and_b32_e32 v3, 8, v3
	v_mov_b32_e32 v0, 0
	v_mad_u32_u24 v185, v28, s37, v190
	v_mov_b32_e32 v28, v0
	v_mov_b32_e32 v30, v0
	v_mov_b32_e32 v31, v0
	v_mov_b32_e32 v32, v0
	v_mov_b32_e32 v33, v0
	v_mov_b32_e32 v34, v0
	v_mov_b32_e32 v35, v0
	v_mov_b32_e32 v36, v0
	v_mov_b32_e32 v37, v0
	v_mov_b32_e32 v38, v0
	v_mov_b32_e32 v39, v0
	v_mov_b32_e32 v40, v0
	v_mov_b32_e32 v41, v0
	v_mov_b32_e32 v42, v0
	v_mov_b32_e32 v43, v0
	v_mov_b32_e32 v44, v0
	v_mov_b32_e32 v45, v0
	v_mov_b32_e32 v46, v0
	v_mov_b32_e32 v47, v0
	v_mov_b32_e32 v48, v0
	v_mov_b32_e32 v49, v0
	v_mov_b32_e32 v50, v0
	v_mov_b32_e32 v51, v0
	v_mov_b32_e32 v52, v0
	v_mov_b32_e32 v53, v0
	v_mov_b32_e32 v54, v0
	v_mov_b32_e32 v55, v0
	v_mov_b32_e32 v56, v0
	v_mov_b32_e32 v57, v0
	v_mov_b32_e32 v58, v0
	s_waitcnt vmcnt(14)
	v_max_u32_e32 v9, v20, v21
	v_mov_b32_e32 v59, v0
	s_waitcnt vmcnt(12)
	v_max3_u32 v9, v9, v22, v23
	v_mov_b32_e32 v60, v0
	s_waitcnt vmcnt(10)
	v_max3_u32 v9, v9, v24, v25
	v_mov_b32_e32 v61, v0
	s_waitcnt vmcnt(8)
	v_max3_u32 v9, v9, v26, v27
	v_mul_f32_e32 v11, 0x4f800000, v9
	v_cmp_gt_f32_e32 vcc, s36, v9
	v_mov_b32_e32 v27, v0
	v_mov_b32_e32 v62, v0
	v_cndmask_b32_e32 v9, v9, v11, vcc
	v_sqrt_f32_e32 v11, v9
	v_mov_b32_e32 v63, v0
	v_mov_b32_e32 v174, v0
	v_mov_b32_e32 v175, v0
	v_add_u32_e32 v23, -1, v11
	v_add_u32_e32 v24, 1, v11
	v_fma_f32 v25, -v23, v11, v9
	v_fma_f32 v26, -v24, v11, v9
	s_waitcnt vmcnt(7)
	v_and_b32_e32 v15, 0xffff0000, v128
	v_lshlrev_b32_e32 v14, 16, v128
	v_mul_f32_e32 v15, v15, v15
	v_lshlrev_b32_e32 v16, 16, v129
	v_fmac_f32_e32 v15, v14, v14
	v_and_b32_e32 v17, 0xffff0000, v129
	v_fmac_f32_e32 v15, v16, v16
	v_lshlrev_b32_e32 v18, 16, v130
	v_cmp_ge_f32_e64 s[6:7], 0, v25
	v_fmac_f32_e32 v15, v17, v17
	v_and_b32_e32 v19, 0xffff0000, v130
	v_cndmask_b32_e64 v11, v11, v23, s[6:7]
	v_cmp_lt_f32_e64 s[6:7], 0, v26
	v_fmac_f32_e32 v15, v18, v18
	v_lshlrev_b32_e32 v20, 16, v131
	v_cndmask_b32_e64 v11, v11, v24, s[6:7]
	v_fmac_f32_e32 v15, v19, v19
	v_and_b32_e32 v21, 0xffff0000, v131
	v_mul_f32_e32 v14, 0x37800000, v11
	v_fmac_f32_e32 v15, v20, v20
	s_waitcnt vmcnt(6)
	v_lshlrev_b32_e32 v22, 16, v132
	v_cndmask_b32_e32 v11, v11, v14, vcc
	v_cmp_class_f32_e32 vcc, v9, v210
	v_fmac_f32_e32 v15, v21, v21
	v_fmac_f32_e32 v15, v22, v22
	v_cndmask_b32_e32 v9, v11, v9, vcc
	v_and_b32_e32 v11, 0xffff0000, v132
	v_fmac_f32_e32 v15, v11, v11
	v_lshlrev_b32_e32 v11, 16, v133
	v_fmac_f32_e32 v15, v11, v11
	v_and_b32_e32 v11, 0xffff0000, v133
	v_fmac_f32_e32 v15, v11, v11
	v_lshlrev_b32_e32 v11, 16, v134
	v_fmac_f32_e32 v15, v11, v11
	v_and_b32_e32 v11, 0xffff0000, v134
	v_fmac_f32_e32 v15, v11, v11
	v_lshlrev_b32_e32 v11, 16, v135
	v_fmac_f32_e32 v15, v11, v11
	v_and_b32_e32 v11, 0xffff0000, v135
	v_fmac_f32_e32 v15, v11, v11
	s_waitcnt vmcnt(5)
; __device__ __forceinline__ int swz23(int r) { return (r & ~12) | ((r & 4) << 1) | ((r & 8) >> 1); }
; #define LOADKV(t) do { \
;     _Pragma("unroll") for (int j = 0; j < NKC; ++j) if (j + 1 < NKC || k1) rk[j] = *(const u32x4*)(kh + (size_t)(t) * 64 * DQK + (size_t)(tid + 512 * j) * 8); \
;     _Pragma("unroll") for (int j = 0; j < NVC; ++j) rv[j] = *(const u32x4*)(vg0 + (size_t)(64 * j) * S + (size_t)(t) * 64); } while (0)
; #define STOREKV(slot) do { \
;     _Pragma("unroll") for (int j = 0; j < NKC; ++j) if (j + 1 < NKC || k1) *(u32x4*)(sK + (slot) * KSB + klo[j]) = rk[j]; \
;     _Pragma("unroll") for (int j = 0; j < NVC; ++j) *(u32x4*)(sV + (slot) * VSB + vlo[j]) = rv[j]; } while (0)
; #define STOREKV(slot) do { int tl_ = TIDV(); asm volatile("" : "+v"(tl_)); const int klo = KLO(tl_), vlo0 = VLO(tl_), vlo1 = vlo0 + 64 * VP; *(u32x4*)(sK + ((slot) * 2) * KSB + klo) = rk[0]; *(u32x4*)(sK + ((slot) * 2 + 1) * KSB + klo) = rk[1]; \
;     *(u32x4*)(sV + (slot) * VSB + vlo0) = rv[0]; *(u32x4*)(sV + (slot) * VSB + vlo1) = rv[1]; } while (0)
; template <int DQK, int DV>
; __device__ __forceinline__ void attn_pass2(const bf16_t* __restrict__ qh, const bf16_t* __restrict__ kh, const bf16_t* __restrict__ vth, int q0, char* smem, f32x16 (&o)[2][DV / 32], float kmax, int wvp) {
;     ...
;   float l_run[2] = {0.f, 0.f}, mref[2];
; #pragma unroll
;   for (int qb = 0; qb < 2; ++qb) {
;     float qq = 0.f;
; #pragma unroll
;     for (int ks = 0; ks < NKS; ++ks)
; #pragma unroll
;       for (int j = 0; j < 8; ++j) { const float t = bf2f((unsigned short)qf[qb][ks][j]); qq += t * t; }
;     { auto rr = __builtin_amdgcn_permlane32_swap(__float_as_uint(qq), __float_as_uint(qq), false, false); qq = __uint_as_float(rr[0]) + __uint_as_float(rr[1]); }
;     mref[qb] = sqrtf(qq) * kmax * 1.01f + 0.01f;
;   }
;   __syncthreads();
;   STOREKV(0);
;   LOADKV(1);
;   const int kofs = swz23(r) * KP + 16 * h, vofs = r * VP + 16 * h;
; #pragma unroll
;   for (int qb = 0; qb < 2; ++qb)
; #pragma unroll
;     for (int ks = 0; ks < NKS; ++ks) asm volatile("" :: "v"(qf[qb][ks]));
	v_lshlrev_b32_e32 v11, 16, v136
	v_fmac_f32_e32 v15, v11, v11
	v_and_b32_e32 v11, 0xffff0000, v136
	v_fmac_f32_e32 v15, v11, v11
	v_lshlrev_b32_e32 v11, 16, v137
	v_fmac_f32_e32 v15, v11, v11
	v_and_b32_e32 v11, 0xffff0000, v137
	v_fmac_f32_e32 v15, v11, v11
	v_lshlrev_b32_e32 v11, 16, v138
	v_fmac_f32_e32 v15, v11, v11
	v_and_b32_e32 v11, 0xffff0000, v138
	v_fmac_f32_e32 v15, v11, v11
	v_lshlrev_b32_e32 v11, 16, v139
	v_fmac_f32_e32 v15, v11, v11
	v_and_b32_e32 v11, 0xffff0000, v139
	v_fmac_f32_e32 v15, v11, v11
	s_waitcnt vmcnt(4)
	v_lshlrev_b32_e32 v11, 16, v140
	v_fmac_f32_e32 v15, v11, v11
	v_and_b32_e32 v11, 0xffff0000, v140
	v_fmac_f32_e32 v15, v11, v11
	v_lshlrev_b32_e32 v11, 16, v141
	v_fmac_f32_e32 v15, v11, v11
	v_and_b32_e32 v11, 0xffff0000, v141
	v_fmac_f32_e32 v15, v11, v11
	v_lshlrev_b32_e32 v11, 16, v142
	v_fmac_f32_e32 v15, v11, v11
	v_and_b32_e32 v11, 0xffff0000, v142
	v_fmac_f32_e32 v15, v11, v11
	v_lshlrev_b32_e32 v11, 16, v143
	v_fmac_f32_e32 v15, v11, v11
	v_and_b32_e32 v11, 0xffff0000, v143
	v_fmac_f32_e32 v15, v11, v11
	v_mov_b32_e32 v11, v15
	s_nop 1
	v_permlane32_swap_b32_e32 v15, v11
	v_add_f32_e32 v11, v15, v11
	v_mul_f32_e32 v14, 0x4f800000, v11
	v_cmp_gt_f32_e32 vcc, s36, v11
	v_lshl_add_u64 v[22:23], s[8:9], 0, v[6:7]
	s_add_u32 s8, s0, s13
	v_cndmask_b32_e32 v11, v11, v14, vcc
	global_load_dwordx4 v[14:17], v[22:23], off
	global_load_dwordx4 v[18:21], v[12:13], off
	v_sqrt_f32_e32 v24, v11
	s_barrier
	v_add_u32_e32 v25, -1, v24
	v_fma_f32 v26, -v25, v24, v11
	v_cmp_ge_f32_e64 s[6:7], 0, v26
	v_add_u32_e32 v26, 1, v24
	s_addc_u32 s9, s1, 0
	v_cndmask_b32_e64 v25, v24, v25, s[6:7]
	v_fma_f32 v24, -v26, v24, v11
	v_cmp_lt_f32_e64 s[6:7], 0, v24
	v_lshl_add_u64 v[170:171], s[8:9], 0, v[6:7]
	s_add_u32 s8, s2, s13
	v_cndmask_b32_e64 v24, v25, v26, s[6:7]
	v_mul_f32_e32 v25, 0x37800000, v24
	s_waitcnt vmcnt(5)
	v_and_b32_e32 v26, 0xffff0000, v144
	v_cndmask_b32_e32 v24, v24, v25, vcc
	v_lshlrev_b32_e32 v25, 16, v144
	v_mul_f32_e32 v26, v26, v26
	v_fmac_f32_e32 v26, v25, v25
	v_lshlrev_b32_e32 v25, 16, v145
	v_fmac_f32_e32 v26, v25, v25
	v_and_b32_e32 v25, 0xffff0000, v145
	v_fmac_f32_e32 v26, v25, v25
	v_lshlrev_b32_e32 v25, 16, v146
	v_fmac_f32_e32 v26, v25, v25
	v_and_b32_e32 v25, 0xffff0000, v146
	v_fmac_f32_e32 v26, v25, v25
	v_lshlrev_b32_e32 v25, 16, v147
	v_fmac_f32_e32 v26, v25, v25
	v_and_b32_e32 v25, 0xffff0000, v147
	v_fmac_f32_e32 v26, v25, v25
	s_waitcnt vmcnt(4)
	v_lshlrev_b32_e32 v25, 16, v148
	v_fmac_f32_e32 v26, v25, v25
	v_and_b32_e32 v25, 0xffff0000, v148
	v_fmac_f32_e32 v26, v25, v25
	v_lshlrev_b32_e32 v25, 16, v149
	v_fmac_f32_e32 v26, v25, v25
	v_and_b32_e32 v25, 0xffff0000, v149
	v_fmac_f32_e32 v26, v25, v25
	v_lshlrev_b32_e32 v25, 16, v150
	v_fmac_f32_e32 v26, v25, v25
	v_and_b32_e32 v25, 0xffff0000, v150
	v_fmac_f32_e32 v26, v25, v25
	v_lshlrev_b32_e32 v25, 16, v151
	v_fmac_f32_e32 v26, v25, v25
	v_and_b32_e32 v25, 0xffff0000, v151
	v_fmac_f32_e32 v26, v25, v25
	s_waitcnt vmcnt(3)
	v_lshlrev_b32_e32 v25, 16, v152
	v_fmac_f32_e32 v26, v25, v25
	v_and_b32_e32 v25, 0xffff0000, v152
	v_fmac_f32_e32 v26, v25, v25
	v_lshlrev_b32_e32 v25, 16, v153
	v_fmac_f32_e32 v26, v25, v25
	v_and_b32_e32 v25, 0xffff0000, v153
	v_fmac_f32_e32 v26, v25, v25
	v_lshlrev_b32_e32 v25, 16, v154
	v_fmac_f32_e32 v26, v25, v25
	v_and_b32_e32 v25, 0xffff0000, v154
	v_fmac_f32_e32 v26, v25, v25
	v_lshlrev_b32_e32 v25, 16, v155
	v_fmac_f32_e32 v26, v25, v25
	v_and_b32_e32 v25, 0xffff0000, v155
	v_fmac_f32_e32 v26, v25, v25
	s_waitcnt vmcnt(2)
	v_lshlrev_b32_e32 v25, 16, v156
	v_fmac_f32_e32 v26, v25, v25
	v_and_b32_e32 v25, 0xffff0000, v156
	v_fmac_f32_e32 v26, v25, v25
	v_lshlrev_b32_e32 v25, 16, v157
	v_fmac_f32_e32 v26, v25, v25
	v_and_b32_e32 v25, 0xffff0000, v157
	v_fmac_f32_e32 v26, v25, v25
	v_lshlrev_b32_e32 v25, 16, v158
	v_fmac_f32_e32 v26, v25, v25
	v_and_b32_e32 v25, 0xffff0000, v158
	v_fmac_f32_e32 v26, v25, v25
	v_lshlrev_b32_e32 v25, 16, v159
	v_fmac_f32_e32 v26, v25, v25
	v_and_b32_e32 v25, 0xffff0000, v159
	v_fmac_f32_e32 v26, v25, v25
	v_mov_b32_e32 v25, v26
	s_nop 1
	v_permlane32_swap_b32_e32 v26, v25
	v_add_f32_e32 v25, v26, v25
	v_mul_f32_e32 v26, 0x4f800000, v25
	v_cmp_gt_f32_e32 vcc, s36, v25
	v_cmp_class_f32_e64 s[6:7], v11, v210
	s_waitcnt vmcnt(1)
	ds_write_b128 v184, v[14:17]
	v_cndmask_b32_e32 v25, v25, v26, vcc
	v_sqrt_f32_e32 v26, v25
	v_cndmask_b32_e64 v11, v24, v11, s[6:7]
	v_mul_f32_e32 v11, v9, v11
	v_fmamk_f32 v182, v11, 0x3f8147ae, v211
	v_add_u32_e32 v11, -1, v26
	v_fma_f32 v24, -v11, v26, v25
	v_cmp_ge_f32_e64 s[6:7], 0, v24
	v_add_u32_e32 v24, 1, v26
	s_addc_u32 s9, s3, 0
	v_cndmask_b32_e64 v11, v26, v11, s[6:7]
	v_fma_f32 v26, -v24, v26, v25
	v_cmp_lt_f32_e64 s[6:7], 0, v26
	v_mov_b32_e32 v6, v0
	v_mov_b32_e32 v7, v0
	v_cndmask_b32_e64 v11, v11, v24, s[6:7]
	v_mul_f32_e32 v24, 0x37800000, v11
	v_cndmask_b32_e32 v11, v11, v24, vcc
	v_cmp_class_f32_e32 vcc, v25, v210
	v_mov_b32_e32 v14, v0
	v_mov_b32_e32 v15, v0
	v_cndmask_b32_e32 v11, v11, v25, vcc
	v_mul_f32_e32 v9, v9, v11
	v_mad_u64_u32 v[168:169], s[6:7], v10, s37, v[8:9]
	v_add_co_u32_e32 v8, vcc, s68, v22
	v_fmamk_f32 v183, v9, 0x3f8147ae, v211
	s_waitcnt vmcnt(0)
	ds_write_b128 v168, v[18:21] offset:18432
	v_addc_co_u32_e32 v9, vcc, 0, v23, vcc
	global_load_dwordx4 v[160:163], v[8:9], off
	global_load_dwordx4 v[164:167], v[12:13], off offset:128
	v_and_b32_e32 v8, 4, v29
	v_or3_b32 v1, v1, v3, v8
	v_mad_u32_u24 v169, v1, s37, v190
	v_and_b32_e32 v1, 7, v2
	v_lshl_or_b32 v4, v1, 4, v4
	s_mov_b32 s6, 0
	v_lshl_add_u64 v[172:173], s[8:9], 0, v[4:5]
	v_mov_b32_e32 v1, v0
	v_mov_b32_e32 v2, v0
	v_mov_b32_e32 v3, v0
	v_mov_b32_e32 v4, v0
	v_mov_b32_e32 v5, v0
	v_mov_b32_e32 v8, v0
	v_mov_b32_e32 v9, v0
	v_mov_b32_e32 v10, v0
	v_mov_b32_e32 v11, v0
	v_mov_b32_e32 v12, v0
	v_mov_b32_e32 v13, v0
	v_mov_b32_e32 v16, v0
	v_mov_b32_e32 v17, v0
	v_mov_b32_e32 v18, v0
	v_mov_b32_e32 v19, v0
	v_mov_b32_e32 v20, v0
	v_mov_b32_e32 v21, v0
	v_mov_b32_e32 v22, v0
	v_mov_b32_e32 v23, v0
	v_mov_b32_e32 v24, v0
	v_mov_b32_e32 v25, v0
	v_mov_b32_e32 v26, v0
	v_mov_b32_e32 v29, v0
	v_max_f32_e32 v236, v182, v183
	v_sub_f32_e32 v236, 0, v236
	v_mov_b32_e32 v237, v236
	v_mov_b32_e32 v238, v236
	v_mov_b32_e32 v239, v236
	v_mov_b32_e32 v240, v236
	v_mov_b32_e32 v241, v236
	v_mov_b32_e32 v242, v236
	v_mov_b32_e32 v243, v236
	v_mov_b32_e32 v244, v236
	v_mov_b32_e32 v245, v236
	v_mov_b32_e32 v246, v236
	v_mov_b32_e32 v247, v236
	v_mov_b32_e32 v248, v236
	v_mov_b32_e32 v249, v236
	v_mov_b32_e32 v250, v236
	v_mov_b32_e32 v251, v236
	s_branch .LBB0_1430
; __device__ __forceinline__ unsigned pk2(float lo, float hi) { f32x2_t v = {lo, hi}; bf16x2_t b = __builtin_convertvector(v, bf16x2_t); return __builtin_bit_cast(unsigned, b); }
; __device__ __forceinline__ float fexp2(float x) { return __builtin_amdgcn_exp2f(x); }
; template <int DQK, int DV>
; __device__ __forceinline__ void attn_pass2(const bf16_t* __restrict__ qh, const bf16_t* __restrict__ kh, const bf16_t* __restrict__ vth, int q0, char* smem, f32x16 (&o)[2][DV / 32], float kmax, int wvp) {
;     ...
;   for (int kt = 0; kt < NT; ++kt) {
;     const int cur = kt & 1;
;     __syncthreads();
;     if (kt + 1 < NT) { STOREKV(cur ^ 1); if (kt + 2 < NT) LOADKV(kt + 2); }
;     f32x16 s[2][2];
;     const char* kb0 = sK + cur * KSB + kofs;
; #pragma unroll
;     for (int ks = 0; ks < NKS; ++ks) {
;       const bf16x8 a0 = *(const bf16x8*)(kb0 + ks * 32), a1 = *(const bf16x8*)(kb0 + 32 * KP + ks * 32);
; #pragma unroll
;       for (int qb = 0; qb < 2; ++qb) {
;         if (ks == 0) {
;           f32x16 z;
; #pragma unroll
;           for (int i = 0; i < 16; ++i) z[i] = 0.f;
;           s[qb][0] = MFMA(a0, qf[qb][0], z); s[qb][1] = MFMA(a1, qf[qb][0], z);
;         } else { s[qb][0] = MFMA(a0, qf[qb][ks], s[qb][0]); s[qb][1] = MFMA(a1, qf[qb][ks], s[qb][1]); }
;       }
;     }
;     __builtin_amdgcn_sched_barrier(0);
; #pragma unroll
;     for (int qb = 0; qb < 2; ++qb) {
;       float rs0 = 0.f, rs1 = 0.f;
; #pragma unroll
;       for (int i = 0; i < 16; ++i) { s[qb][0][i] = fexp2(s[qb][0][i] - mref[qb]); s[qb][1][i] = fexp2(s[qb][1][i] - mref[qb]); rs0 += s[qb][0][i]; rs1 += s[qb][1][i]; }
;       l_run[qb] += rs0 + rs1;
;     }
;     const char* vb0 = sV + cur * VSB + vofs;
; #pragma unroll
;     for (int kb = 0; kb < 2; ++kb)
; #pragma unroll
;       for (int s2 = 0; s2 < 2; ++s2) {
;         bf16x8 pq[2];
; #pragma unroll
;         for (int qb = 0; qb < 2; ++qb) {
;           u32x4 w;
;           w.x = pk2(s[qb][kb][8 * s2 + 0], s[qb][kb][8 * s2 + 1]); w.y = pk2(s[qb][kb][8 * s2 + 2], s[qb][kb][8 * s2 + 3]);
;           w.z = pk2(s[qb][kb][8 * s2 + 4], s[qb][kb][8 * s2 + 5]); w.w = pk2(s[qb][kb][8 * s2 + 6], s[qb][kb][8 * s2 + 7]);
;           pq[qb] = __builtin_bit_cast(bf16x8, w);
;         }
; #pragma unroll
;         for (int eb = 0; eb < NEB; ++eb) {
;           const bf16x8 a = *(const bf16x8*)(vb0 + eb * 32 * VP + (32 * kb + 16 * s2) * 2);
.LBB0_1429:
	s_mulk_i32 s7, 0x2400
	v_add_u32_e32 v180, s7, v169
	ds_read_b128 v[64:67], v180
	ds_read_b128 v[176:179], v180 offset:32
	ds_read_b128 v[68:71], v180 offset:4608
	ds_read_b128 v[192:195], v180 offset:4640
	s_add_i32 s6, s6, 1
	s_waitcnt lgkmcnt(3)
	v_mfma_f32_32x32x16_bf16 v[112:127], v[64:67], v[128:131], v[236:251]
	s_waitcnt lgkmcnt(1)
	v_mfma_f32_32x32x16_bf16 v[96:111], v[68:71], v[128:131], v[236:251]
	v_mfma_f32_32x32x16_bf16 v[80:95], v[64:67], v[144:147], v[236:251]
	v_mfma_f32_32x32x16_bf16 v[64:79], v[68:71], v[144:147], v[236:251]
	v_mfma_f32_32x32x16_bf16 v[112:127], v[176:179], v[132:135], v[112:127]
	s_waitcnt lgkmcnt(0)
	v_mfma_f32_32x32x16_bf16 v[96:111], v[192:195], v[132:135], v[96:111]
	v_mfma_f32_32x32x16_bf16 v[80:95], v[176:179], v[148:151], v[80:95]
	v_mfma_f32_32x32x16_bf16 v[64:79], v[192:195], v[148:151], v[64:79]
	ds_read_b128 v[176:179], v180 offset:64
	ds_read_b128 v[192:195], v180 offset:96
	ds_read_b128 v[196:199], v180 offset:4672
	ds_read_b128 v[200:203], v180 offset:4704
	s_waitcnt lgkmcnt(3)
	v_mfma_f32_32x32x16_bf16 v[112:127], v[176:179], v[136:139], v[112:127]
	s_waitcnt lgkmcnt(1)
	v_mfma_f32_32x32x16_bf16 v[96:111], v[196:199], v[136:139], v[96:111]
	v_mfma_f32_32x32x16_bf16 v[80:95], v[176:179], v[152:155], v[80:95]
	v_mfma_f32_32x32x16_bf16 v[64:79], v[196:199], v[152:155], v[64:79]
	v_mfma_f32_32x32x16_bf16 v[112:127], v[192:195], v[140:143], v[112:127]
	s_waitcnt lgkmcnt(0)
	v_mfma_f32_32x32x16_bf16 v[96:111], v[200:203], v[140:143], v[96:111]
	v_mfma_f32_32x32x16_bf16 v[80:95], v[192:195], v[156:159], v[80:95]
	v_mfma_f32_32x32x16_bf16 v[64:79], v[200:203], v[156:159], v[64:79]
	s_nop 9
	v_exp_f32_e32 v186, v96
	v_exp_f32_e32 v97, v97
	v_exp_f32_e32 v177, v112
	v_add_f32_e32 v112, 0, v186
	v_exp_f32_e32 v113, v113
	v_exp_f32_e32 v179, v114
	v_exp_f32_e32 v187, v98
	v_add_f32_e32 v98, v97, v112
	v_exp_f32_e32 v115, v115
	v_exp_f32_e32 v190, v99
	v_exp_f32_e32 v204, v100
	v_add_f32_e32 v96, 0, v177
	v_exp_f32_e32 v99, v116
	v_exp_f32_e32 v117, v117
	v_add_f32_e32 v96, v113, v96
	v_exp_f32_e32 v101, v101
	v_add_f32_e32 v96, v179, v96
	v_exp_f32_e32 v181, v118
	v_add_f32_e32 v96, v115, v96
	v_add_f32_e32 v96, v99, v96
	v_add_f32_e32 v96, v117, v96
	v_add_f32_e32 v112, v181, v96
	v_exp_f32_e32 v176, v119
	v_exp_f32_e32 v178, v103
	v_add_f32_e32 v98, v187, v98
	v_exp_f32_e32 v205, v102
	v_exp_f32_e32 v180, v120
	v_exp_f32_e32 v96, v104
	v_exp_f32_e32 v104, v123
	v_add_f32_e32 v98, v190, v98
	v_exp_f32_e32 v100, v106
	v_exp_f32_e32 v106, v107
	v_add_f32_e32 v98, v204, v98
	v_exp_f32_e32 v118, v124
	v_add_f32_e32 v98, v101, v98
	v_exp_f32_e32 v120, v108
	v_add_f32_e32 v102, v205, v98
	v_exp_f32_e32 v124, v125
	v_exp_f32_e32 v116, v121
	v_exp_f32_e32 v108, v109
	v_exp_f32_e32 v114, v105
	v_exp_f32_e32 v98, v122
	v_exp_f32_e32 v122, v126
	v_exp_f32_e32 v110, v110
	v_exp_f32_e32 v126, v127
	v_exp_f32_e32 v103, v80
	v_exp_f32_e32 v107, v64
	v_exp_f32_e32 v109, v81
	v_exp_f32_e32 v65, v65
	v_exp_f32_e32 v121, v66
	v_add_f32_e32 v80, 0, v103
	v_add_f32_e32 v105, 0, v107
	v_add_f32_e32 v66, v109, v80
	v_add_f32_e32 v80, v65, v105
	v_add_f32_e32 v206, v121, v80
	v_exp_f32_e32 v207, v83
	v_add_u32_e32 v209, s7, v185
	v_exp_f32_e32 v64, v111
	v_exp_f32_e32 v111, v82
	v_exp_f32_e32 v208, v84
	ds_read_b128 v[80:83], v209 offset:18432
	ds_read_b128 v[196:199], v209 offset:18464
	ds_read_b128 v[200:203], v209 offset:23040
	v_exp_f32_e32 v212, v85
	v_exp_f32_e32 v213, v86
	v_cvt_pk_bf16_f32 v192, v177, v113
	v_exp_f32_e32 v177, v87
	v_cvt_pk_bf16_f32 v84, v103, v109
	v_exp_f32_e32 v109, v67
	v_add_f32_e32 v66, v111, v66
	v_cvt_pk_bf16_f32 v85, v111, v207
	v_exp_f32_e32 v111, v68
	v_cvt_pk_bf16_f32 v195, v181, v176
	v_exp_f32_e32 v181, v88
	v_cvt_pk_bf16_f32 v194, v99, v117
	v_exp_f32_e32 v117, v89
	v_cvt_pk_bf16_f32 v193, v179, v115
	v_cvt_pk_bf16_f32 v86, v208, v212
	v_cvt_pk_bf16_f32 v87, v213, v177
	v_exp_f32_e32 v99, v90
	s_waitcnt lgkmcnt(2)
; __device__ __forceinline__ unsigned pk2(float lo, float hi) { f32x2_t v = {lo, hi}; bf16x2_t b = __builtin_convertvector(v, bf16x2_t); return __builtin_bit_cast(unsigned, b); }
; __device__ __forceinline__ float fexp2(float x) { return __builtin_amdgcn_exp2f(x); }
; #define MFMA(a, b, c) __builtin_amdgcn_mfma_f32_32x32x16_bf16((a), (b), (c), 0, 0, 0)
; template <int DQK, int DV>
; __device__ __forceinline__ void attn_pass2(const bf16_t* __restrict__ qh, const bf16_t* __restrict__ kh, const bf16_t* __restrict__ vth, int q0, char* smem, f32x16 (&o)[2][DV / 32], float kmax, int wvp) {
;     ...
;       for (int i = 0; i < 16; ++i) { s[qb][0][i] = fexp2(s[qb][0][i] - mref[qb]); s[qb][1][i] = fexp2(s[qb][1][i] - mref[qb]); rs0 += s[qb][0][i]; rs1 += s[qb][1][i]; }
;       l_run[qb] += rs0 + rs1;
;     }
;     const char* vb0 = sV + cur * VSB + vofs;
; #pragma unroll
;     for (int kb = 0; kb < 2; ++kb)
; #pragma unroll
;       for (int s2 = 0; s2 < 2; ++s2) {
;         bf16x8 pq[2];
; #pragma unroll
;         for (int qb = 0; qb < 2; ++qb) {
;           u32x4 w;
;           w.x = pk2(s[qb][kb][8 * s2 + 0], s[qb][kb][8 * s2 + 1]); w.y = pk2(s[qb][kb][8 * s2 + 2], s[qb][kb][8 * s2 + 3]);
;           w.z = pk2(s[qb][kb][8 * s2 + 4], s[qb][kb][8 * s2 + 5]); w.w = pk2(s[qb][kb][8 * s2 + 6], s[qb][kb][8 * s2 + 7]);
;           pq[qb] = __builtin_bit_cast(bf16x8, w);
;         }
; #pragma unroll
;         for (int eb = 0; eb < NEB; ++eb) {
;           const bf16x8 a = *(const bf16x8*)(vb0 + eb * 32 * VP + (32 * kb + 16 * s2) * 2);
; #pragma unroll
;           for (int qb = 0; qb < 2; ++qb) o[qb][eb] = MFMA(a, pq[qb], o[qb][eb]);
;         }
;       }
;   }
	v_mfma_f32_32x32x16_bf16 v[48:63], v[80:83], v[192:195], v[48:63]
	v_exp_f32_e32 v105, v91
	v_exp_f32_e32 v119, v92
	v_exp_f32_e32 v125, v93
	v_mfma_f32_32x32x16_bf16 v[16:31], v[80:83], v[84:87], v[16:31]
	ds_read_b128 v[80:83], v209 offset:23072
	v_exp_f32_e32 v123, v94
	v_exp_f32_e32 v92, v69
	v_exp_f32_e32 v127, v95
	s_waitcnt lgkmcnt(1)
	v_mfma_f32_32x32x16_bf16 v[0:15], v[200:203], v[84:87], v[0:15]
	v_exp_f32_e32 v93, v70
	v_add_f32_e32 v66, v207, v66
	v_add_f32_e32 v67, v109, v206
	v_add_f32_e32 v66, v208, v66
	v_add_f32_e32 v67, v111, v67
	v_add_f32_e32 v66, v212, v66
	v_add_f32_e32 v67, v92, v67
	v_mfma_f32_32x32x16_bf16 v[32:47], v[200:203], v[192:195], v[32:47]
	v_cvt_pk_bf16_f32 v84, v180, v116
	v_cvt_pk_bf16_f32 v85, v98, v104
	v_cvt_pk_bf16_f32 v86, v118, v124
	v_cvt_pk_bf16_f32 v87, v122, v126
	v_cvt_pk_bf16_f32 v88, v181, v117
	v_cvt_pk_bf16_f32 v89, v99, v105
	v_cvt_pk_bf16_f32 v90, v119, v125
	v_cvt_pk_bf16_f32 v91, v123, v127
	v_add_f32_e32 v113, v213, v66
	v_add_f32_e32 v103, v93, v67
	ds_read_b128 v[66:69], v209 offset:18496
	v_mfma_f32_32x32x16_bf16 v[48:63], v[196:199], v[84:87], v[48:63]
	v_exp_f32_e32 v179, v71
	v_mov_b32_e32 v70, v72
	v_exp_f32_e32 v115, v73
	v_cvt_pk_bf16_f32 v71, v121, v109
	v_cvt_pk_bf16_f32 v72, v111, v92
	v_cvt_pk_bf16_f32 v73, v93, v179
	v_mfma_f32_32x32x16_bf16 v[16:31], v[196:199], v[88:91], v[16:31]
	v_lshl_add_u64 v[170:171], v[170:171], 0, s[52:53]
	s_cmpk_lg_i32 s6, 0x80
	v_lshl_add_u64 v[172:173], v[172:173], 0, s[54:55]
	s_waitcnt lgkmcnt(1)
	v_mfma_f32_32x32x16_bf16 v[0:15], v[80:83], v[88:91], v[0:15]
	ds_read_b128 v[88:91], v209 offset:23104
	v_mfma_f32_32x32x16_bf16 v[32:47], v[80:83], v[84:87], v[32:47]
	v_cvt_pk_bf16_f32 v80, v186, v97
	v_exp_f32_e32 v97, v70
	v_cvt_pk_bf16_f32 v70, v107, v65
	v_cvt_pk_bf16_f32 v81, v187, v190
	v_cvt_pk_bf16_f32 v82, v204, v101
	v_cvt_pk_bf16_f32 v83, v205, v178
	v_exp_f32_e32 v101, v74
	ds_read_b128 v[84:87], v209 offset:18528
	s_waitcnt lgkmcnt(2)
	v_mfma_f32_32x32x16_bf16 v[48:63], v[66:69], v[80:83], v[48:63]
	v_exp_f32_e32 v107, v75
	v_exp_f32_e32 v121, v76
	v_exp_f32_e32 v109, v77
	v_exp_f32_e32 v111, v78
	v_mfma_f32_32x32x16_bf16 v[16:31], v[66:69], v[70:73], v[16:31]
	ds_read_b128 v[66:69], v209 offset:23136
	v_exp_f32_e32 v65, v79
	v_pk_add_f32 v[74:75], v[178:179], v[102:103]
	s_nop 0
	v_pk_add_f32 v[74:75], v[96:97], v[74:75]
	s_waitcnt lgkmcnt(2)
	v_mfma_f32_32x32x16_bf16 v[32:47], v[88:91], v[80:83], v[32:47]
	v_add_f32_e64 v80, v114, v74
	v_add_f32_e64 v81, v115, v75
	v_cvt_pk_bf16_f32 v74, v97, v115
	v_cvt_pk_bf16_f32 v75, v101, v107
	v_add_f32_e64 v80, v100, v80
	v_add_f32_e64 v81, v101, v81
	v_pk_add_f32 v[80:81], v[106:107], v[80:81]
	v_mfma_f32_32x32x16_bf16 v[0:15], v[88:91], v[70:73], v[0:15]
	v_add_f32_e64 v70, v176, v112
	v_add_f32_e64 v71, v177, v113
	v_cvt_pk_bf16_f32 v72, v120, v108
	v_add_f32_e64 v76, v180, v70
	v_add_f32_e64 v77, v181, v71
	v_cvt_pk_bf16_f32 v70, v96, v114
	v_cvt_pk_bf16_f32 v71, v100, v106
	v_cvt_pk_bf16_f32 v73, v110, v64
	v_pk_add_f32 v[78:79], v[116:117], v[76:77]
	v_cvt_pk_bf16_f32 v76, v121, v109
	v_cvt_pk_bf16_f32 v77, v111, v65
	s_waitcnt lgkmcnt(1)
	v_mfma_f32_32x32x16_bf16 v[48:63], v[84:87], v[70:73], v[48:63]
	v_add_f32_e64 v78, v98, v78
	v_add_f32_e64 v79, v99, v79
	v_add_f32_e64 v80, v120, v80
	v_add_f32_e64 v81, v121, v81
	v_add_f32_e64 v78, v104, v78
	v_add_f32_e64 v79, v105, v79
	v_pk_add_f32 v[78:79], v[118:119], v[78:79]
	s_nop 0
	v_pk_add_f32 v[78:79], v[124:125], v[78:79]
	v_mfma_f32_32x32x16_bf16 v[16:31], v[84:87], v[74:77], v[16:31]
	s_waitcnt lgkmcnt(0)
	v_mfma_f32_32x32x16_bf16 v[32:47], v[66:69], v[70:73], v[32:47]
	v_add_f32_e64 v70, v108, v80
	v_add_f32_e64 v71, v109, v81
	v_add_f32_e64 v72, v122, v78
	v_add_f32_e64 v73, v123, v79
	v_add_f32_e64 v70, v110, v70
	v_add_f32_e64 v71, v111, v71
	v_pk_add_f32 v[72:73], v[126:127], v[72:73]
	v_pk_add_f32 v[64:65], v[64:65], v[70:71]
	s_nop 0
	v_pk_add_f32 v[64:65], v[72:73], v[64:65]
	v_mfma_f32_32x32x16_bf16 v[0:15], v[66:69], v[74:77], v[0:15]
	v_add_f32_e64 v174, v174, v64
	v_add_f32_e64 v175, v175, v65
	s_cbranch_scc0 .LBB0_1433

; __device__ __forceinline__ int swz23(int r) { return (r & ~12) | ((r & 4) << 1) | ((r & 8) >> 1); }
; #define LOADKV(t) do { \
;     _Pragma("unroll") for (int j = 0; j < NKC; ++j) if (j + 1 < NKC || k1) rk[j] = *(const u32x4*)(kh + (size_t)(t) * 64 * DQK + (size_t)(tid + 512 * j) * 8); \
;     _Pragma("unroll") for (int j = 0; j < NVC; ++j) rv[j] = *(const u32x4*)(vg0 + (size_t)(64 * j) * S + (size_t)(t) * 64); } while (0)
; #define STOREKV(slot) do { \
;     _Pragma("unroll") for (int j = 0; j < NKC; ++j) if (j + 1 < NKC || k1) *(u32x4*)(sK + (slot) * KSB + klo[j]) = rk[j]; \
;     _Pragma("unroll") for (int j = 0; j < NVC; ++j) *(u32x4*)(sV + (slot) * VSB + vlo[j]) = rv[j]; } while (0)
; #define STOREKV(slot) do { int tl_ = TIDV(); asm volatile("" : "+v"(tl_)); const int klo = KLO(tl_), vlo0 = VLO(tl_), vlo1 = vlo0 + 64 * VP; *(u32x4*)(sK + ((slot) * 2) * KSB + klo) = rk[0]; *(u32x4*)(sK + ((slot) * 2 + 1) * KSB + klo) = rk[1]; \
;     *(u32x4*)(sV + (slot) * VSB + vlo0) = rv[0]; *(u32x4*)(sV + (slot) * VSB + vlo1) = rv[1]; } while (0)
; template <int DQK, int DV>
; __device__ __forceinline__ void attn_pass2(const bf16_t* __restrict__ qh, const bf16_t* __restrict__ kh, const bf16_t* __restrict__ vth, int q0, char* smem, f32x16 (&o)[2][DV / 32], float kmax, int wvp) {
;     ...
;   LOADKV(0);
; #pragma unroll
;   for (int qb = 0; qb < 2; ++qb)
; #pragma unroll
;     for (int eb = 0; eb < NEB; ++eb)
; #pragma unroll
;       for (int i = 0; i < 16; ++i) o[qb][eb][i] = 0.f;
;   float l_run[2] = {0.f, 0.f}, mref[2];
; #pragma unroll
;   for (int qb = 0; qb < 2; ++qb) {
;     float qq = 0.f;
; #pragma unroll
;     for (int ks = 0; ks < NKS; ++ks)
; #pragma unroll
;       for (int j = 0; j < 8; ++j) { const float t = bf2f((unsigned short)qf[qb][ks][j]); qq += t * t; }
;     { auto rr = __builtin_amdgcn_permlane32_swap(__float_as_uint(qq), __float_as_uint(qq), false, false); qq = __uint_as_float(rr[0]) + __uint_as_float(rr[1]); }
;     mref[qb] = sqrtf(qq) * kmax * 1.01f + 0.01f;
;   }
;   __syncthreads();
;   STOREKV(0);
;   LOADKV(1);
;   const int kofs = swz23(r) * KP + 16 * h, vofs = r * VP + 16 * h;
; #pragma unroll
;   for (int qb = 0; qb < 2; ++qb)
; #pragma unroll
;     for (int ks = 0; ks < NKS; ++ks) asm volatile("" :: "v"(qf[qb][ks]));
.LBB0_1443:
	s_or_b64 exec, exec, s[8:9]
	global_load_dwordx4 v[184:187], v[20:21], off offset:128
	v_cndmask_b32_e64 v2, v11, v23, s[10:11]
	v_cndmask_b32_e64 v2, v2, v24, s[12:13]
	v_mul_f32_e32 v3, 0x37800000, v2
	v_cndmask_b32_e64 v2, v2, v3, s[6:7]
	v_cndmask_b32_e64 v3, v25, v26, s[16:17]
	v_cndmask_b32_e64 v3, v3, v30, s[22:23]
	v_mul_f32_e32 v4, 0x37800000, v3
	v_cndmask_b32_e64 v3, v3, v4, s[14:15]
	v_cndmask_b32_e64 v4, v28, v29, s[20:21]
	v_cmp_class_f32_e64 s[6:7], v9, v210
	v_cndmask_b32_e64 v4, v4, v31, s[24:25]
	v_mul_f32_e32 v5, 0x37800000, v4
	v_cndmask_b32_e64 v2, v2, v9, s[6:7]
	v_cmp_class_f32_e64 s[6:7], v19, v210
	v_cndmask_b32_e64 v4, v4, v5, s[18:19]
	v_mad_u32_u24 v216, v22, s37, v10
	v_cndmask_b32_e64 v3, v3, v19, s[6:7]
	v_cmp_class_f32_e64 s[6:7], v27, v210
	v_mul_f32_e32 v3, v2, v3
	v_fmamk_f32 v193, v3, 0x3f8147ae, v211
	v_cndmask_b32_e64 v4, v4, v27, s[6:7]
	v_mul_f32_e32 v2, v2, v4
	s_and_b32 s6, s73, 15
	v_lshlrev_b32_e32 v3, 1, v22
	v_lshrrev_b32_e32 v4, 1, v8
	v_fmamk_f32 v214, v2, 0x3f8147ae, v211
	s_lshl_b32 s50, s6, 20
	s_mul_i32 s6, s6, 0x180000
	v_and_b32_e32 v2, 19, v8
	v_and_b32_e32 v3, 8, v3
	v_and_b32_e32 v4, 4, v4
	v_or3_b32 v2, v2, v3, v4
	v_and_b32_e32 v4, 7, v8
	s_add_u32 s6, s4, s6
	v_mad_u32_u24 v215, v2, s72, v10
	v_lshl_add_u64 v[2:3], s[50:51], 0, v[14:15]
	v_lshlrev_b32_e32 v190, 4, v4
	s_addc_u32 s7, s5, 0
	v_lshl_add_u64 v[2:3], v[2:3], 0, v[190:191]
	v_lshl_add_u64 v[198:199], s[6:7], 0, v[0:1]
	v_mov_b32_e32 v0, 0
	v_lshl_add_u64 v[194:195], s[44:45], 0, v[2:3]
	v_lshl_add_u64 v[196:197], s[6:7], 0, v[12:13]
	s_mov_b32 s10, 0
	s_mov_b64 s[6:7], 0
	v_mov_b32_e32 v1, v0
	v_mov_b32_e32 v2, v0
	v_mov_b32_e32 v3, v0
	v_mov_b32_e32 v4, v0
	v_mov_b32_e32 v5, v0
	v_mov_b32_e32 v6, v0
	v_mov_b32_e32 v7, v0
	v_mov_b32_e32 v8, v0
	v_mov_b32_e32 v9, v0
	v_mov_b32_e32 v10, v0
	v_mov_b32_e32 v11, v0
	v_mov_b32_e32 v12, v0
	v_mov_b32_e32 v13, v0
	v_mov_b32_e32 v14, v0
	v_mov_b32_e32 v15, v0
	v_mov_b32_e32 v16, v0
	v_mov_b32_e32 v17, v0
	v_mov_b32_e32 v18, v0
	v_mov_b32_e32 v19, v0
	v_mov_b32_e32 v20, v0
	v_mov_b32_e32 v21, v0
	v_mov_b32_e32 v22, v0
	v_mov_b32_e32 v23, v0
	v_mov_b32_e32 v24, v0
	v_mov_b32_e32 v25, v0
	v_mov_b32_e32 v26, v0
	v_mov_b32_e32 v27, v0
	v_mov_b32_e32 v28, v0
	v_mov_b32_e32 v29, v0
	v_mov_b32_e32 v30, v0
	v_mov_b32_e32 v31, v0
	v_mov_b32_e32 v32, v0
	v_mov_b32_e32 v33, v0
	v_mov_b32_e32 v34, v0
	v_mov_b32_e32 v35, v0
	v_mov_b32_e32 v36, v0
	v_mov_b32_e32 v37, v0
	v_mov_b32_e32 v38, v0
	v_mov_b32_e32 v39, v0
	v_mov_b32_e32 v40, v0
	v_mov_b32_e32 v41, v0
	v_mov_b32_e32 v42, v0
	v_mov_b32_e32 v43, v0
	v_mov_b32_e32 v44, v0
	v_mov_b32_e32 v45, v0
	v_mov_b32_e32 v46, v0
	v_mov_b32_e32 v47, v0
	v_mov_b32_e32 v48, v0
	v_mov_b32_e32 v49, v0
	v_mov_b32_e32 v50, v0
	v_mov_b32_e32 v51, v0
	v_mov_b32_e32 v52, v0
	v_mov_b32_e32 v53, v0
	v_mov_b32_e32 v54, v0
	v_mov_b32_e32 v55, v0
	v_mov_b32_e32 v56, v0
	v_mov_b32_e32 v57, v0
	v_mov_b32_e32 v58, v0
	v_mov_b32_e32 v59, v0
	v_mov_b32_e32 v60, v0
	v_mov_b32_e32 v61, v0
	v_mov_b32_e32 v62, v0
	v_mov_b32_e32 v63, v0
	v_mov_b32_e32 v200, v0
	v_mov_b32_e32 v201, v0
	v_max_f32_e32 v236, v193, v214
	v_sub_f32_e32 v236, 0, v236
	v_mov_b32_e32 v237, v236
	v_mov_b32_e32 v238, v236
	v_mov_b32_e32 v239, v236
	v_mov_b32_e32 v240, v236
	v_mov_b32_e32 v241, v236
	v_mov_b32_e32 v242, v236
	v_mov_b32_e32 v243, v236
	v_mov_b32_e32 v244, v236
	v_mov_b32_e32 v245, v236
	v_mov_b32_e32 v246, v236
	v_mov_b32_e32 v247, v236
	v_mov_b32_e32 v248, v236
	v_mov_b32_e32 v249, v236
	v_mov_b32_e32 v250, v236
	v_mov_b32_e32 v251, v236
	s_branch .LBB0_1446

; __device__ __forceinline__ float fexp2(float x) { return __builtin_amdgcn_exp2f(x); }
; #define MFMA(a, b, c) __builtin_amdgcn_mfma_f32_32x32x16_bf16((a), (b), (c), 0, 0, 0)
; #define LOADKV(t) do { \
;     _Pragma("unroll") for (int j = 0; j < NKC; ++j) if (j + 1 < NKC || k1) rk[j] = *(const u32x4*)(kh + (size_t)(t) * 64 * DQK + (size_t)(tid + 512 * j) * 8); \
;     _Pragma("unroll") for (int j = 0; j < NVC; ++j) rv[j] = *(const u32x4*)(vg0 + (size_t)(64 * j) * S + (size_t)(t) * 64); } while (0)
; #define STOREKV(slot) do { \
;     _Pragma("unroll") for (int j = 0; j < NKC; ++j) if (j + 1 < NKC || k1) *(u32x4*)(sK + (slot) * KSB + klo[j]) = rk[j]; \
;     _Pragma("unroll") for (int j = 0; j < NVC; ++j) *(u32x4*)(sV + (slot) * VSB + vlo[j]) = rv[j]; } while (0)
; template <int DQK, int DV>
; __device__ __forceinline__ void attn_pass2(const bf16_t* __restrict__ qh, const bf16_t* __restrict__ kh, const bf16_t* __restrict__ vth, int q0, char* smem, f32x16 (&o)[2][DV / 32], float kmax, int wvp) {
;     ...
;   for (int kt = 0; kt < NT; ++kt) {
;     const int cur = kt & 1;
;     __syncthreads();
;     if (kt + 1 < NT) { STOREKV(cur ^ 1); if (kt + 2 < NT) LOADKV(kt + 2); }
;     f32x16 s[2][2];
;     const char* kb0 = sK + cur * KSB + kofs;
; #pragma unroll
;     for (int ks = 0; ks < NKS; ++ks) {
;       const bf16x8 a0 = *(const bf16x8*)(kb0 + ks * 32), a1 = *(const bf16x8*)(kb0 + 32 * KP + ks * 32);
; #pragma unroll
;       for (int qb = 0; qb < 2; ++qb) {
;         if (ks == 0) {
;           f32x16 z;
; #pragma unroll
;           for (int i = 0; i < 16; ++i) z[i] = 0.f;
;           s[qb][0] = MFMA(a0, qf[qb][0], z); s[qb][1] = MFMA(a1, qf[qb][0], z);
;         } else { s[qb][0] = MFMA(a0, qf[qb][ks], s[qb][0]); s[qb][1] = MFMA(a1, qf[qb][ks], s[qb][1]); }
;       }
;     }
;     __builtin_amdgcn_sched_barrier(0);
; #pragma unroll
;     for (int qb = 0; qb < 2; ++qb) {
;       float rs0 = 0.f, rs1 = 0.f;
; #pragma unroll
;       for (int i = 0; i < 16; ++i) { s[qb][0][i] = fexp2(s[qb][0][i] - mref[qb]); s[qb][1][i] = fexp2(s[qb][1][i] - mref[qb]); rs0 += s[qb][0][i]; rs1 += s[qb][1][i]; }
;       l_run[qb] += rs0 + rs1;
;     }
;     const char* vb0 = sV + cur * VSB + vofs;
; #pragma unroll
;     for (int kb = 0; kb < 2; ++kb)
; #pragma unroll
.LBB0_1445:
	s_mul_i32 s8, s11, 0x3400
	v_add_u32_e32 v190, s8, v215
	ds_read_b128 v[64:67], v190
	ds_read_b128 v[202:205], v190 offset:32
	ds_read_b128 v[68:71], v190 offset:6656
	ds_read_b128 v[206:209], v190 offset:6688
	s_waitcnt lgkmcnt(3)
	v_mfma_f32_32x32x16_bf16 v[112:127], v[64:67], v[128:131], v[236:251]
	s_waitcnt lgkmcnt(1)
	v_mfma_f32_32x32x16_bf16 v[96:111], v[68:71], v[128:131], v[236:251]
	v_mfma_f32_32x32x16_bf16 v[80:95], v[64:67], v[152:155], v[236:251]
	v_mfma_f32_32x32x16_bf16 v[64:79], v[68:71], v[152:155], v[236:251]
	v_mfma_f32_32x32x16_bf16 v[112:127], v[202:205], v[132:135], v[112:127]
	s_waitcnt lgkmcnt(0)
	v_mfma_f32_32x32x16_bf16 v[96:111], v[206:209], v[132:135], v[96:111]
	v_mfma_f32_32x32x16_bf16 v[80:95], v[202:205], v[156:159], v[80:95]
	v_mfma_f32_32x32x16_bf16 v[64:79], v[206:209], v[156:159], v[64:79]
	ds_read_b128 v[202:205], v190 offset:64
	ds_read_b128 v[206:209], v190 offset:96
	ds_read_b128 v[218:221], v190 offset:6720
	ds_read_b128 v[222:225], v190 offset:6752
	s_waitcnt lgkmcnt(3)
	v_mfma_f32_32x32x16_bf16 v[112:127], v[202:205], v[136:139], v[112:127]
	s_waitcnt lgkmcnt(1)
	v_mfma_f32_32x32x16_bf16 v[96:111], v[218:221], v[136:139], v[96:111]
	v_mfma_f32_32x32x16_bf16 v[80:95], v[202:205], v[160:163], v[80:95]
	v_mfma_f32_32x32x16_bf16 v[64:79], v[218:221], v[160:163], v[64:79]
	v_mfma_f32_32x32x16_bf16 v[112:127], v[206:209], v[140:143], v[112:127]
	s_waitcnt lgkmcnt(0)
	v_mfma_f32_32x32x16_bf16 v[96:111], v[222:225], v[140:143], v[96:111]
	v_mfma_f32_32x32x16_bf16 v[80:95], v[206:209], v[164:167], v[80:95]
	ds_read_b128 v[202:205], v190 offset:128
	ds_read_b128 v[206:209], v190 offset:160
	v_mfma_f32_32x32x16_bf16 v[64:79], v[222:225], v[164:167], v[64:79]
	ds_read_b128 v[218:221], v190 offset:6784
	ds_read_b128 v[222:225], v190 offset:6816
	s_waitcnt lgkmcnt(3)
	v_mfma_f32_32x32x16_bf16 v[112:127], v[202:205], v[144:147], v[112:127]
	s_waitcnt lgkmcnt(1)
	v_mfma_f32_32x32x16_bf16 v[96:111], v[218:221], v[144:147], v[96:111]
	v_mfma_f32_32x32x16_bf16 v[80:95], v[202:205], v[168:171], v[80:95]
	v_mfma_f32_32x32x16_bf16 v[64:79], v[218:221], v[168:171], v[64:79]
	v_mfma_f32_32x32x16_bf16 v[112:127], v[206:209], v[148:151], v[112:127]
	s_waitcnt lgkmcnt(0)
	v_mfma_f32_32x32x16_bf16 v[96:111], v[222:225], v[148:151], v[96:111]
	v_mfma_f32_32x32x16_bf16 v[80:95], v[206:209], v[172:175], v[80:95]
	v_mfma_f32_32x32x16_bf16 v[64:79], v[222:225], v[172:175], v[64:79]
	s_nop 9
	v_exp_f32_e32 v96, v96
	v_exp_f32_e32 v112, v112
	v_exp_f32_e32 v208, v97
	v_exp_f32_e32 v204, v113
	v_exp_f32_e32 v227, v99
	v_exp_f32_e32 v114, v114
	v_exp_f32_e32 v116, v116
	v_add_f32_e32 v202, 0, v96
	v_exp_f32_e32 v217, v98
	v_exp_f32_e32 v100, v100
	v_add_f32_e32 v190, 0, v112
	v_add_f32_e32 v98, v208, v202
	v_exp_f32_e32 v202, v117
	v_add_f32_e32 v97, v204, v190
	v_exp_f32_e32 v190, v115
	v_exp_f32_e32 v228, v101
	v_exp_f32_e32 v118, v118
	v_add_f32_e32 v98, v217, v98
	v_exp_f32_e32 v229, v102
	v_add_f32_e32 v97, v114, v97
	v_add_f32_e32 v98, v227, v98
	v_add_f32_e32 v97, v190, v97
	v_add_f32_e32 v98, v100, v98
	v_add_f32_e32 v97, v116, v97
	v_add_f32_e32 v98, v228, v98
	v_add_f32_e32 v97, v202, v97
	v_add_f32_e32 v113, v229, v98
	v_add_f32_e32 v115, v118, v97
	v_exp_f32_e32 v203, v119
	v_exp_f32_e32 v119, v121
	v_exp_f32_e32 v117, v105
	v_exp_f32_e32 v99, v122
	v_exp_f32_e32 v101, v106
	v_exp_f32_e32 v205, v103
	v_exp_f32_e32 v103, v123
	v_exp_f32_e32 v105, v107
	v_exp_f32_e32 v107, v124
	v_exp_f32_e32 v121, v108
	v_exp_f32_e32 v125, v125
	v_exp_f32_e32 v109, v109
	v_exp_f32_e32 v123, v126
	v_exp_f32_e32 v209, v110
	v_exp_f32_e32 v127, v127
	v_exp_f32_e32 v98, v80
	v_exp_f32_e32 v102, v81
	v_exp_f32_e32 v108, v65
	v_exp_f32_e32 v207, v120
	v_exp_f32_e32 v97, v104
	v_exp_f32_e32 v104, v64
	v_exp_f32_e32 v106, v82
	v_exp_f32_e32 v111, v111
	v_add_f32_e32 v64, 0, v98
	v_exp_f32_e32 v110, v66
	v_add_f32_e32 v64, v102, v64
	v_add_f32_e32 v80, 0, v104
	v_add_f32_e32 v120, v106, v64
	s_mulk_i32 s11, 0x2400
	v_add_f32_e32 v65, v108, v80
	v_exp_f32_e32 v231, v83
	v_add_u32_e32 v233, s11, v216
	v_add_f32_e32 v230, v110, v65
	v_mov_b32_e32 v122, v67
	v_exp_f32_e32 v232, v84
	ds_read_b128 v[64:67], v233 offset:26624
	ds_read_b128 v[218:221], v233 offset:26656
	v_exp_f32_e32 v234, v85
	ds_read_b128 v[222:225], v233 offset:31232
	v_exp_f32_e32 v235, v86
	v_cvt_pk_bf16_f32 v82, v116, v202
	v_exp_f32_e32 v202, v87
	v_cvt_pk_bf16_f32 v80, v112, v204
	v_cvt_pk_bf16_f32 v81, v114, v190
	v_cvt_pk_bf16_f32 v83, v118, v203
	v_cvt_pk_bf16_f32 v84, v98, v102
	v_cvt_pk_bf16_f32 v85, v106, v231
	v_cvt_pk_bf16_f32 v86, v232, v234
	v_cvt_pk_bf16_f32 v87, v235, v202
	s_waitcnt lgkmcnt(2)
; __device__ __forceinline__ unsigned pk2(float lo, float hi) { f32x2_t v = {lo, hi}; bf16x2_t b = __builtin_convertvector(v, bf16x2_t); return __builtin_bit_cast(unsigned, b); }
; __device__ __forceinline__ float fexp2(float x) { return __builtin_amdgcn_exp2f(x); }
; #define MFMA(a, b, c) __builtin_amdgcn_mfma_f32_32x32x16_bf16((a), (b), (c), 0, 0, 0)
; template <int DQK, int DV>
; __device__ __forceinline__ void attn_pass2(const bf16_t* __restrict__ qh, const bf16_t* __restrict__ kh, const bf16_t* __restrict__ vth, int q0, char* smem, f32x16 (&o)[2][DV / 32], float kmax, int wvp) {
;     ...
;       for (int i = 0; i < 16; ++i) { s[qb][0][i] = fexp2(s[qb][0][i] - mref[qb]); s[qb][1][i] = fexp2(s[qb][1][i] - mref[qb]); rs0 += s[qb][0][i]; rs1 += s[qb][1][i]; }
;       l_run[qb] += rs0 + rs1;
;     }
;     const char* vb0 = sV + cur * VSB + vofs;
; #pragma unroll
;     for (int kb = 0; kb < 2; ++kb)
; #pragma unroll
;       for (int s2 = 0; s2 < 2; ++s2) {
;         bf16x8 pq[2];
; #pragma unroll
;         for (int qb = 0; qb < 2; ++qb) {
;           u32x4 w;
;           w.x = pk2(s[qb][kb][8 * s2 + 0], s[qb][kb][8 * s2 + 1]); w.y = pk2(s[qb][kb][8 * s2 + 2], s[qb][kb][8 * s2 + 3]);
;           w.z = pk2(s[qb][kb][8 * s2 + 4], s[qb][kb][8 * s2 + 5]); w.w = pk2(s[qb][kb][8 * s2 + 6], s[qb][kb][8 * s2 + 7]);
;           pq[qb] = __builtin_bit_cast(bf16x8, w);
;         }
; #pragma unroll
;         for (int eb = 0; eb < NEB; ++eb) {
;           const bf16x8 a = *(const bf16x8*)(vb0 + eb * 32 * VP + (32 * kb + 16 * s2) * 2);
; #pragma unroll
;           for (int qb = 0; qb < 2; ++qb) o[qb][eb] = MFMA(a, pq[qb], o[qb][eb]);
;         }
;       }
;   }
	v_mfma_f32_32x32x16_bf16 v[48:63], v[64:67], v[80:83], v[48:63]
	v_exp_f32_e32 v116, v122
	s_add_u32 s6, s6, 0x3000
	s_addc_u32 s7, s7, 0
	s_add_i32 s10, s10, 1
	v_mfma_f32_32x32x16_bf16 v[16:31], v[64:67], v[84:87], v[16:31]
	v_exp_f32_e32 v190, v68
	v_exp_f32_e32 v206, v88
	ds_read_b128 v[64:67], v233 offset:31264
	v_exp_f32_e32 v118, v89
	s_waitcnt lgkmcnt(1)
	v_mfma_f32_32x32x16_bf16 v[32:47], v[222:225], v[80:83], v[32:47]
	v_exp_f32_e32 v98, v90
	v_exp_f32_e32 v102, v91
	v_exp_f32_e32 v106, v92
	v_exp_f32_e32 v124, v93
	v_mfma_f32_32x32x16_bf16 v[0:15], v[222:225], v[84:87], v[0:15]
	v_exp_f32_e32 v122, v94
	v_exp_f32_e32 v89, v69
	v_exp_f32_e32 v126, v95
	v_exp_f32_e32 v90, v70
	v_cvt_pk_bf16_f32 v80, v207, v119
	v_cvt_pk_bf16_f32 v81, v99, v103
	v_cvt_pk_bf16_f32 v82, v107, v125
	v_cvt_pk_bf16_f32 v83, v123, v127
	v_add_f32_e32 v68, v231, v120
	v_add_f32_e32 v88, v116, v230
	v_mfma_f32_32x32x16_bf16 v[48:63], v[218:221], v[80:83], v[48:63]
	v_add_f32_e32 v68, v232, v68
	v_add_f32_e32 v88, v190, v88
	v_add_f32_e32 v68, v234, v68
	v_add_f32_e32 v69, v89, v88
	v_cvt_pk_bf16_f32 v84, v206, v118
	v_cvt_pk_bf16_f32 v85, v98, v102
	v_cvt_pk_bf16_f32 v86, v106, v124
	s_waitcnt lgkmcnt(0)
	v_mfma_f32_32x32x16_bf16 v[32:47], v[64:67], v[80:83], v[32:47]
	v_exp_f32_e32 v204, v71
	v_cvt_pk_bf16_f32 v87, v122, v126
	v_add_f32_e32 v114, v235, v68
	v_add_f32_e32 v112, v90, v69
	ds_read_b128 v[68:71], v233 offset:26688
	ds_read_b128 v[80:83], v233 offset:26720
	v_mfma_f32_32x32x16_bf16 v[16:31], v[218:221], v[84:87], v[16:31]
	s_cmp_lg_u32 s6, 0x180000
	v_lshl_add_u64 v[194:195], v[194:195], 0, s[54:55]
	v_mfma_f32_32x32x16_bf16 v[0:15], v[64:67], v[84:87], v[0:15]
	v_cvt_pk_bf16_f32 v86, v190, v89
	v_cvt_pk_bf16_f32 v87, v90, v204
	ds_read_b128 v[88:91], v233 offset:31296
	v_cvt_pk_bf16_f32 v64, v96, v208
	v_cvt_pk_bf16_f32 v65, v217, v227
	v_cvt_pk_bf16_f32 v66, v100, v228
	v_cvt_pk_bf16_f32 v67, v229, v205
	v_cvt_pk_bf16_f32 v84, v104, v108
	v_cvt_pk_bf16_f32 v85, v110, v116
	s_waitcnt lgkmcnt(2)
	v_mfma_f32_32x32x16_bf16 v[48:63], v[68:71], v[64:67], v[48:63]
	v_exp_f32_e32 v96, v72
	v_exp_f32_e32 v116, v73
	v_exp_f32_e32 v120, v76
	v_pk_add_f32 v[72:73], v[204:205], v[112:113]
	v_mfma_f32_32x32x16_bf16 v[16:31], v[68:71], v[84:87], v[16:31]
	v_exp_f32_e32 v100, v74
	v_exp_f32_e32 v104, v75
	ds_read_b128 v[68:71], v233 offset:31328
	v_pk_add_f32 v[72:73], v[96:97], v[72:73]
	s_waitcnt lgkmcnt(1)
	v_mfma_f32_32x32x16_bf16 v[32:47], v[88:91], v[64:67], v[32:47]
	v_exp_f32_e32 v108, v77
	v_exp_f32_e32 v208, v78
	v_exp_f32_e32 v110, v79
	v_pk_add_f32 v[64:65], v[202:203], v[114:115]
	v_mfma_f32_32x32x16_bf16 v[0:15], v[88:91], v[84:87], v[0:15]
	v_add_f32_e64 v74, v206, v64
	v_add_f32_e64 v75, v207, v65
	v_cvt_pk_bf16_f32 v64, v97, v117
	v_cvt_pk_bf16_f32 v65, v101, v105
	v_cvt_pk_bf16_f32 v66, v121, v109
	v_cvt_pk_bf16_f32 v67, v209, v111
	v_pk_add_f32 v[76:77], v[118:119], v[74:75]
	v_pk_add_f32 v[78:79], v[116:117], v[72:73]
	v_cvt_pk_bf16_f32 v72, v96, v116
	v_cvt_pk_bf16_f32 v73, v100, v104
	v_cvt_pk_bf16_f32 v74, v120, v108
	v_cvt_pk_bf16_f32 v75, v208, v110
	v_mfma_f32_32x32x16_bf16 v[48:63], v[80:83], v[64:67], v[48:63]
	v_add_f32_e64 v76, v98, v76
	v_add_f32_e64 v77, v99, v77
	v_add_f32_e64 v78, v100, v78
	v_add_f32_e64 v79, v101, v79
	v_add_f32_e64 v76, v102, v76
	v_add_f32_e64 v77, v103, v77
	v_pk_add_f32 v[78:79], v[104:105], v[78:79]
	v_pk_add_f32 v[76:77], v[106:107], v[76:77]
	v_pk_add_f32 v[78:79], v[120:121], v[78:79]
	v_pk_add_f32 v[76:77], v[124:125], v[76:77]
	v_mfma_f32_32x32x16_bf16 v[16:31], v[80:83], v[72:75], v[16:31]
	s_waitcnt lgkmcnt(0)
	v_mfma_f32_32x32x16_bf16 v[32:47], v[68:71], v[64:67], v[32:47]
	v_add_f32_e64 v64, v108, v78
	v_add_f32_e64 v65, v109, v79
	v_add_f32_e64 v66, v122, v76
	v_add_f32_e64 v67, v123, v77
	v_add_f32_e64 v64, v208, v64
	v_add_f32_e64 v65, v209, v65
	v_pk_add_f32 v[66:67], v[126:127], v[66:67]
	v_pk_add_f32 v[64:65], v[110:111], v[64:65]
	s_nop 0
	v_pk_add_f32 v[64:65], v[66:67], v[64:65]
	v_mfma_f32_32x32x16_bf16 v[0:15], v[68:71], v[72:75], v[0:15]
	v_add_f32_e64 v200, v200, v64
	v_add_f32_e64 v201, v201, v65
	s_cbranch_scc0 .LBB0_1425
